# gate/up epilogue: store addresses by strength reduction (one 64-bit add per store instead of two 64-bit mads + moves)
# baseline (speedup 1.0000x reference)
; __device__ __forceinline__ unsigned cvt_pk_bf16(float lo, float hi) { unsigned r; asm volatile("v_cvt_pk_bf16_f32 %0, %1, %2" : "=v"(r) : "v"(lo), "v"(hi)); return r; }
;     __device__ __forceinline__ void operator()(const f32x4 (&acc)[2][2][4][2], const Unit& u, int wr, int wc, int fr, int fq) const {
;     ...
; #pragma unroll
;         for (int ai = 0; ai < 2; ++ai)
; #pragma unroll
;             for (int m = 0; m < 4; ++m) { const int row = row0 + ai * HALF + m * 16; const float r = rs[ai * 4 + m];
;                 float hv[8];
; #pragma unroll
;                 for (int n = 0; n < 2; ++n)
; #pragma unroll
;                     for (int e = 0; e < 4; ++e) { const float g = acc[ai][0][m][n][e] * r, up = acc[ai][1][m][n][e] * r;
;                         const float sg = g * __builtin_amdgcn_rcpf(1.0f + __builtin_amdgcn_exp2f(g * -1.4426950408889634f)); hv[n * 4 + e] = sg * up; }
;                 u32x4 w; w.x = cvt_pk_bf16(hv[0], hv[1]); w.y = cvt_pk_bf16(hv[2], hv[3]); w.z = cvt_pk_bf16(hv[4], hv[5]); w.w = cvt_pk_bf16(hv[6], hv[7]);
;                 *(u32x4*)(H + (size_t)row * 2816 + col0) = w; }
.LBB0_104:
	s_mov_b32 s100, 0xbfb8aa3b
	s_mov_b32 s101, 1.0
	s_waitcnt lgkmcnt(0)
	v_mov_b32_e32 v192, 0x16000
	v_mov_b32_e32 v193, 0
	v_mov_b32_e32 v194, 0x6e000
	v_mov_b32_e32 v195, 0
	v_pk_mul_f32 v[132:133], v[132:133], v[0:1] op_sel_hi:[1,0]
	v_pk_mul_f32 v[134:135], v[134:135], v[0:1] op_sel_hi:[1,0]
	v_pk_mul_f32 v[124:125], v[124:125], v[0:1] op_sel_hi:[1,0]
	v_pk_mul_f32 v[126:127], v[126:127], v[0:1] op_sel_hi:[1,0]
	v_pk_mul_f32 v[128:129], v[128:129], v[0:1] op_sel_hi:[1,0]
	v_pk_mul_f32 v[130:131], v[130:131], v[0:1] op_sel_hi:[1,0]
	v_pk_mul_f32 v[120:121], v[120:121], v[0:1] op_sel_hi:[1,0]
	v_pk_mul_f32 v[122:123], v[122:123], v[0:1] op_sel_hi:[1,0]
	v_pk_mul_f32 v[182:183], v[132:133], s[100:101] op_sel_hi:[1,0]
	v_pk_mul_f32 v[184:185], v[134:135], s[100:101] op_sel_hi:[1,0]
	v_pk_mul_f32 v[186:187], v[124:125], s[100:101] op_sel_hi:[1,0]
	v_pk_mul_f32 v[188:189], v[126:127], s[100:101] op_sel_hi:[1,0]
	v_exp_f32_e32 v182, v182
	v_exp_f32_e32 v183, v183
	v_exp_f32_e32 v184, v184
	v_exp_f32_e32 v185, v185
	v_exp_f32_e32 v186, v186
	v_exp_f32_e32 v187, v187
	v_exp_f32_e32 v188, v188
	v_exp_f32_e32 v189, v189
	v_pk_add_f32 v[182:183], v[182:183], s[100:101] op_sel:[0,1]
	v_pk_add_f32 v[184:185], v[184:185], s[100:101] op_sel:[0,1]
	v_pk_add_f32 v[186:187], v[186:187], s[100:101] op_sel:[0,1]
	v_pk_add_f32 v[188:189], v[188:189], s[100:101] op_sel:[0,1]
	v_rcp_f32_e32 v182, v182
	v_rcp_f32_e32 v183, v183
	v_rcp_f32_e32 v184, v184
	v_rcp_f32_e32 v185, v185
	v_rcp_f32_e32 v186, v186
	v_rcp_f32_e32 v187, v187
	v_rcp_f32_e32 v188, v188
	v_rcp_f32_e32 v189, v189
	v_pk_mul_f32 v[182:183], v[132:133], v[182:183]
	v_pk_mul_f32 v[184:185], v[134:135], v[184:185]
	v_pk_mul_f32 v[186:187], v[124:125], v[186:187]
	v_pk_mul_f32 v[188:189], v[126:127], v[188:189]
	v_pk_mul_f32 v[182:183], v[128:129], v[182:183]
	v_pk_mul_f32 v[184:185], v[130:131], v[184:185]
	v_pk_mul_f32 v[186:187], v[120:121], v[186:187]
	v_pk_mul_f32 v[188:189], v[122:123], v[188:189]
	v_cvt_pk_bf16_f32 v124, v182, v183
	v_cvt_pk_bf16_f32 v125, v184, v185
	v_cvt_pk_bf16_f32 v126, v186, v187
	v_cvt_pk_bf16_f32 v127, v188, v189
	v_lshl_or_b32 v176, s42, 7, v179
	v_ashrrev_i32_e32 v177, 31, v176
	s_andn2_b64 vcc, exec, s[4:5]
	v_mov_b64_e32 v[120:121], s[10:11]
	v_mad_u64_u32 v[128:129], s[22:23], v158, s91, v[120:121]
	v_mov_b32_e32 v122, v129
	v_mad_u64_u32 v[122:123], s[22:23], v159, s91, v[122:123]
	v_mov_b32_e32 v129, v122
	v_lshlrev_b64 v[122:123], 1, v[176:177]
	v_lshl_add_u64 v[128:129], v[128:129], 0, v[122:123]
	global_store_dwordx4 v[128:129], v[124:127], off
	s_nop 1
	v_pk_mul_f32 v[116:117], v[116:117], v[0:1] op_sel:[0,1]
	v_pk_mul_f32 v[118:119], v[118:119], v[0:1] op_sel:[0,1]
	v_pk_mul_f32 v[108:109], v[108:109], v[0:1] op_sel:[0,1]
	v_pk_mul_f32 v[110:111], v[110:111], v[0:1] op_sel:[0,1]
	v_pk_mul_f32 v[112:113], v[112:113], v[0:1] op_sel:[0,1]
	v_pk_mul_f32 v[114:115], v[114:115], v[0:1] op_sel:[0,1]
	v_pk_mul_f32 v[104:105], v[104:105], v[0:1] op_sel:[0,1]
	v_pk_mul_f32 v[106:107], v[106:107], v[0:1] op_sel:[0,1]
	v_pk_mul_f32 v[182:183], v[116:117], s[100:101] op_sel_hi:[1,0]
	v_pk_mul_f32 v[184:185], v[118:119], s[100:101] op_sel_hi:[1,0]
	v_pk_mul_f32 v[186:187], v[108:109], s[100:101] op_sel_hi:[1,0]
	v_pk_mul_f32 v[188:189], v[110:111], s[100:101] op_sel_hi:[1,0]
	v_exp_f32_e32 v182, v182
	v_exp_f32_e32 v183, v183
	v_exp_f32_e32 v184, v184
	v_exp_f32_e32 v185, v185
	v_exp_f32_e32 v186, v186
	v_exp_f32_e32 v187, v187
	v_exp_f32_e32 v188, v188
	v_exp_f32_e32 v189, v189
	v_pk_add_f32 v[182:183], v[182:183], s[100:101] op_sel:[0,1]
	v_pk_add_f32 v[184:185], v[184:185], s[100:101] op_sel:[0,1]
	v_pk_add_f32 v[186:187], v[186:187], s[100:101] op_sel:[0,1]
	v_pk_add_f32 v[188:189], v[188:189], s[100:101] op_sel:[0,1]
	v_rcp_f32_e32 v182, v182
	v_rcp_f32_e32 v183, v183
	v_rcp_f32_e32 v184, v184
	v_rcp_f32_e32 v185, v185
	v_rcp_f32_e32 v186, v186
	v_rcp_f32_e32 v187, v187
	v_rcp_f32_e32 v188, v188
	v_rcp_f32_e32 v189, v189
	v_pk_mul_f32 v[182:183], v[116:117], v[182:183]
	v_pk_mul_f32 v[184:185], v[118:119], v[184:185]
	v_pk_mul_f32 v[186:187], v[108:109], v[186:187]
	v_pk_mul_f32 v[188:189], v[110:111], v[188:189]
	v_pk_mul_f32 v[182:183], v[112:113], v[182:183]
	v_pk_mul_f32 v[184:185], v[114:115], v[184:185]
	v_pk_mul_f32 v[186:187], v[104:105], v[186:187]
	v_pk_mul_f32 v[188:189], v[106:107], v[188:189]
	v_cvt_pk_bf16_f32 v104, v182, v183
	v_cvt_pk_bf16_f32 v105, v184, v185
	v_cvt_pk_bf16_f32 v106, v186, v187
	v_cvt_pk_bf16_f32 v107, v188, v189
	v_lshl_add_u64 v[190:191], v[128:129], 0, v[192:193]
	global_store_dwordx4 v[190:191], v[104:107], off
	s_nop 1
	v_pk_mul_f32 v[100:101], v[100:101], v[2:3] op_sel_hi:[1,0]
	v_pk_mul_f32 v[102:103], v[102:103], v[2:3] op_sel_hi:[1,0]
	v_pk_mul_f32 v[92:93], v[92:93], v[2:3] op_sel_hi:[1,0]
	v_pk_mul_f32 v[94:95], v[94:95], v[2:3] op_sel_hi:[1,0]
	v_pk_mul_f32 v[96:97], v[96:97], v[2:3] op_sel_hi:[1,0]
	v_pk_mul_f32 v[98:99], v[98:99], v[2:3] op_sel_hi:[1,0]
	v_pk_mul_f32 v[88:89], v[88:89], v[2:3] op_sel_hi:[1,0]
	v_pk_mul_f32 v[90:91], v[90:91], v[2:3] op_sel_hi:[1,0]
	v_pk_mul_f32 v[182:183], v[100:101], s[100:101] op_sel_hi:[1,0]
	v_pk_mul_f32 v[184:185], v[102:103], s[100:101] op_sel_hi:[1,0]
	v_pk_mul_f32 v[186:187], v[92:93], s[100:101] op_sel_hi:[1,0]
	v_pk_mul_f32 v[188:189], v[94:95], s[100:101] op_sel_hi:[1,0]
	v_exp_f32_e32 v182, v182
	v_exp_f32_e32 v183, v183
	v_exp_f32_e32 v184, v184
	v_exp_f32_e32 v185, v185
	v_exp_f32_e32 v186, v186
	v_exp_f32_e32 v187, v187
	v_exp_f32_e32 v188, v188
	v_exp_f32_e32 v189, v189
	v_pk_add_f32 v[182:183], v[182:183], s[100:101] op_sel:[0,1]
; __device__ __forceinline__ unsigned cvt_pk_bf16(float lo, float hi) { unsigned r; asm volatile("v_cvt_pk_bf16_f32 %0, %1, %2" : "=v"(r) : "v"(lo), "v"(hi)); return r; }
;     __device__ __forceinline__ void operator()(const f32x4 (&acc)[2][2][4][2], const Unit& u, int wr, int wc, int fr, int fq) const {
;     ...
;             for (int m = 0; m < 4; ++m) { const int row = row0 + ai * HALF + m * 16; const float r = rs[ai * 4 + m];
;                 float hv[8];
; #pragma unroll
;                 for (int n = 0; n < 2; ++n)
; #pragma unroll
;                     for (int e = 0; e < 4; ++e) { const float g = acc[ai][0][m][n][e] * r, up = acc[ai][1][m][n][e] * r;
;                         const float sg = g * __builtin_amdgcn_rcpf(1.0f + __builtin_amdgcn_exp2f(g * -1.4426950408889634f)); hv[n * 4 + e] = sg * up; }
;                 u32x4 w; w.x = cvt_pk_bf16(hv[0], hv[1]); w.y = cvt_pk_bf16(hv[2], hv[3]); w.z = cvt_pk_bf16(hv[4], hv[5]); w.w = cvt_pk_bf16(hv[6], hv[7]);
;                 *(u32x4*)(H + (size_t)row * 2816 + col0) = w; }
	v_pk_add_f32 v[184:185], v[184:185], s[100:101] op_sel:[0,1]
	v_pk_add_f32 v[186:187], v[186:187], s[100:101] op_sel:[0,1]
	v_pk_add_f32 v[188:189], v[188:189], s[100:101] op_sel:[0,1]
	v_rcp_f32_e32 v182, v182
	v_rcp_f32_e32 v183, v183
	v_rcp_f32_e32 v184, v184
	v_rcp_f32_e32 v185, v185
	v_rcp_f32_e32 v186, v186
	v_rcp_f32_e32 v187, v187
	v_rcp_f32_e32 v188, v188
	v_rcp_f32_e32 v189, v189
	v_pk_mul_f32 v[182:183], v[100:101], v[182:183]
	v_pk_mul_f32 v[184:185], v[102:103], v[184:185]
	v_pk_mul_f32 v[186:187], v[92:93], v[186:187]
	v_pk_mul_f32 v[188:189], v[94:95], v[188:189]
	v_pk_mul_f32 v[182:183], v[96:97], v[182:183]
	v_pk_mul_f32 v[184:185], v[98:99], v[184:185]
	v_pk_mul_f32 v[186:187], v[88:89], v[186:187]
	v_pk_mul_f32 v[188:189], v[90:91], v[188:189]
	v_cvt_pk_bf16_f32 v88, v182, v183
	v_cvt_pk_bf16_f32 v89, v184, v185
	v_cvt_pk_bf16_f32 v90, v186, v187
	v_cvt_pk_bf16_f32 v91, v188, v189
	v_lshl_add_u64 v[190:191], v[190:191], 0, v[192:193]
	global_store_dwordx4 v[190:191], v[88:91], off
	s_nop 1
	v_pk_mul_f32 v[84:85], v[84:85], v[2:3] op_sel:[0,1]
	v_pk_mul_f32 v[86:87], v[86:87], v[2:3] op_sel:[0,1]
	v_pk_mul_f32 v[76:77], v[76:77], v[2:3] op_sel:[0,1]
	v_pk_mul_f32 v[78:79], v[78:79], v[2:3] op_sel:[0,1]
	v_pk_mul_f32 v[80:81], v[80:81], v[2:3] op_sel:[0,1]
	v_pk_mul_f32 v[82:83], v[82:83], v[2:3] op_sel:[0,1]
	v_pk_mul_f32 v[72:73], v[72:73], v[2:3] op_sel:[0,1]
	v_pk_mul_f32 v[74:75], v[74:75], v[2:3] op_sel:[0,1]
	v_pk_mul_f32 v[182:183], v[84:85], s[100:101] op_sel_hi:[1,0]
	v_pk_mul_f32 v[184:185], v[86:87], s[100:101] op_sel_hi:[1,0]
	v_pk_mul_f32 v[186:187], v[76:77], s[100:101] op_sel_hi:[1,0]
	v_pk_mul_f32 v[188:189], v[78:79], s[100:101] op_sel_hi:[1,0]
	v_exp_f32_e32 v182, v182
	v_exp_f32_e32 v183, v183
	v_exp_f32_e32 v184, v184
	v_exp_f32_e32 v185, v185
	v_exp_f32_e32 v186, v186
	v_exp_f32_e32 v187, v187
	v_exp_f32_e32 v188, v188
	v_exp_f32_e32 v189, v189
	v_pk_add_f32 v[182:183], v[182:183], s[100:101] op_sel:[0,1]
	v_pk_add_f32 v[184:185], v[184:185], s[100:101] op_sel:[0,1]
	v_pk_add_f32 v[186:187], v[186:187], s[100:101] op_sel:[0,1]
	v_pk_add_f32 v[188:189], v[188:189], s[100:101] op_sel:[0,1]
	v_rcp_f32_e32 v182, v182
	v_rcp_f32_e32 v183, v183
	v_rcp_f32_e32 v184, v184
	v_rcp_f32_e32 v185, v185
	v_rcp_f32_e32 v186, v186
	v_rcp_f32_e32 v187, v187
	v_rcp_f32_e32 v188, v188
	v_rcp_f32_e32 v189, v189
	v_pk_mul_f32 v[182:183], v[84:85], v[182:183]
	v_pk_mul_f32 v[184:185], v[86:87], v[184:185]
	v_pk_mul_f32 v[186:187], v[76:77], v[186:187]
	v_pk_mul_f32 v[188:189], v[78:79], v[188:189]
	v_pk_mul_f32 v[182:183], v[80:81], v[182:183]
	v_pk_mul_f32 v[184:185], v[82:83], v[184:185]
	v_pk_mul_f32 v[186:187], v[72:73], v[186:187]
	v_pk_mul_f32 v[188:189], v[74:75], v[188:189]
	v_cvt_pk_bf16_f32 v0, v182, v183
	v_cvt_pk_bf16_f32 v1, v184, v185
	v_cvt_pk_bf16_f32 v2, v186, v187
	v_cvt_pk_bf16_f32 v3, v188, v189
	v_lshl_add_u64 v[190:191], v[190:191], 0, v[192:193]
	global_store_dwordx4 v[190:191], v[0:3], off
	s_nop 1
	v_pk_mul_f32 v[68:69], v[68:69], v[4:5] op_sel_hi:[1,0]
	v_pk_mul_f32 v[70:71], v[70:71], v[4:5] op_sel_hi:[1,0]
	v_pk_mul_f32 v[60:61], v[60:61], v[4:5] op_sel_hi:[1,0]
	v_pk_mul_f32 v[62:63], v[62:63], v[4:5] op_sel_hi:[1,0]
	v_pk_mul_f32 v[64:65], v[64:65], v[4:5] op_sel_hi:[1,0]
	v_pk_mul_f32 v[66:67], v[66:67], v[4:5] op_sel_hi:[1,0]
	v_pk_mul_f32 v[56:57], v[56:57], v[4:5] op_sel_hi:[1,0]
	v_pk_mul_f32 v[58:59], v[58:59], v[4:5] op_sel_hi:[1,0]
	v_pk_mul_f32 v[182:183], v[68:69], s[100:101] op_sel_hi:[1,0]
	v_pk_mul_f32 v[184:185], v[70:71], s[100:101] op_sel_hi:[1,0]
	v_pk_mul_f32 v[186:187], v[60:61], s[100:101] op_sel_hi:[1,0]
	v_pk_mul_f32 v[188:189], v[62:63], s[100:101] op_sel_hi:[1,0]
	v_exp_f32_e32 v182, v182
	v_exp_f32_e32 v183, v183
	v_exp_f32_e32 v184, v184
	v_exp_f32_e32 v185, v185
	v_exp_f32_e32 v186, v186
	v_exp_f32_e32 v187, v187
	v_exp_f32_e32 v188, v188
	v_exp_f32_e32 v189, v189
	v_pk_add_f32 v[182:183], v[182:183], s[100:101] op_sel:[0,1]
	v_pk_add_f32 v[184:185], v[184:185], s[100:101] op_sel:[0,1]
	v_pk_add_f32 v[186:187], v[186:187], s[100:101] op_sel:[0,1]
	v_pk_add_f32 v[188:189], v[188:189], s[100:101] op_sel:[0,1]
	v_rcp_f32_e32 v182, v182
	v_rcp_f32_e32 v183, v183
	v_rcp_f32_e32 v184, v184
	v_rcp_f32_e32 v185, v185
	v_rcp_f32_e32 v186, v186
	v_rcp_f32_e32 v187, v187
	v_rcp_f32_e32 v188, v188
	v_rcp_f32_e32 v189, v189
	v_pk_mul_f32 v[182:183], v[68:69], v[182:183]
	v_pk_mul_f32 v[184:185], v[70:71], v[184:185]
	v_pk_mul_f32 v[186:187], v[60:61], v[186:187]
	v_pk_mul_f32 v[188:189], v[62:63], v[188:189]
	v_pk_mul_f32 v[182:183], v[64:65], v[182:183]
	v_pk_mul_f32 v[184:185], v[66:67], v[184:185]
	v_pk_mul_f32 v[186:187], v[56:57], v[186:187]
	v_pk_mul_f32 v[188:189], v[58:59], v[188:189]
	v_cvt_pk_bf16_f32 v0, v182, v183
	v_cvt_pk_bf16_f32 v1, v184, v185
	v_cvt_pk_bf16_f32 v2, v186, v187
	v_cvt_pk_bf16_f32 v3, v188, v189
	v_lshl_add_u64 v[190:191], v[190:191], 0, v[194:195]
	global_store_dwordx4 v[190:191], v[0:3], off
	s_nop 1
	v_pk_mul_f32 v[52:53], v[52:53], v[4:5] op_sel:[0,1]
	v_pk_mul_f32 v[54:55], v[54:55], v[4:5] op_sel:[0,1]
	v_pk_mul_f32 v[44:45], v[44:45], v[4:5] op_sel:[0,1]
	v_pk_mul_f32 v[46:47], v[46:47], v[4:5] op_sel:[0,1]
	v_pk_mul_f32 v[48:49], v[48:49], v[4:5] op_sel:[0,1]
	v_pk_mul_f32 v[50:51], v[50:51], v[4:5] op_sel:[0,1]
	v_pk_mul_f32 v[40:41], v[40:41], v[4:5] op_sel:[0,1]
	v_pk_mul_f32 v[42:43], v[42:43], v[4:5] op_sel:[0,1]
	v_pk_mul_f32 v[182:183], v[52:53], s[100:101] op_sel_hi:[1,0]
	v_pk_mul_f32 v[184:185], v[54:55], s[100:101] op_sel_hi:[1,0]
; __device__ __forceinline__ unsigned cvt_pk_bf16(float lo, float hi) { unsigned r; asm volatile("v_cvt_pk_bf16_f32 %0, %1, %2" : "=v"(r) : "v"(lo), "v"(hi)); return r; }
;     __device__ __forceinline__ void operator()(const f32x4 (&acc)[2][2][4][2], const Unit& u, int wr, int wc, int fr, int fq) const {
;     ...
;             for (int m = 0; m < 4; ++m) { const int row = row0 + ai * HALF + m * 16; const float r = rs[ai * 4 + m];
;                 float hv[8];
; #pragma unroll
;                 for (int n = 0; n < 2; ++n)
; #pragma unroll
;                     for (int e = 0; e < 4; ++e) { const float g = acc[ai][0][m][n][e] * r, up = acc[ai][1][m][n][e] * r;
;                         const float sg = g * __builtin_amdgcn_rcpf(1.0f + __builtin_amdgcn_exp2f(g * -1.4426950408889634f)); hv[n * 4 + e] = sg * up; }
;                 u32x4 w; w.x = cvt_pk_bf16(hv[0], hv[1]); w.y = cvt_pk_bf16(hv[2], hv[3]); w.z = cvt_pk_bf16(hv[4], hv[5]); w.w = cvt_pk_bf16(hv[6], hv[7]);
;                 *(u32x4*)(H + (size_t)row * 2816 + col0) = w; }
	v_pk_mul_f32 v[186:187], v[44:45], s[100:101] op_sel_hi:[1,0]
	v_pk_mul_f32 v[188:189], v[46:47], s[100:101] op_sel_hi:[1,0]
	v_exp_f32_e32 v182, v182
	v_exp_f32_e32 v183, v183
	v_exp_f32_e32 v184, v184
	v_exp_f32_e32 v185, v185
	v_exp_f32_e32 v186, v186
	v_exp_f32_e32 v187, v187
	v_exp_f32_e32 v188, v188
	v_exp_f32_e32 v189, v189
	v_pk_add_f32 v[182:183], v[182:183], s[100:101] op_sel:[0,1]
	v_pk_add_f32 v[184:185], v[184:185], s[100:101] op_sel:[0,1]
	v_pk_add_f32 v[186:187], v[186:187], s[100:101] op_sel:[0,1]
	v_pk_add_f32 v[188:189], v[188:189], s[100:101] op_sel:[0,1]
	v_rcp_f32_e32 v182, v182
	v_rcp_f32_e32 v183, v183
	v_rcp_f32_e32 v184, v184
	v_rcp_f32_e32 v185, v185
	v_rcp_f32_e32 v186, v186
	v_rcp_f32_e32 v187, v187
	v_rcp_f32_e32 v188, v188
	v_rcp_f32_e32 v189, v189
	v_pk_mul_f32 v[182:183], v[52:53], v[182:183]
	v_pk_mul_f32 v[184:185], v[54:55], v[184:185]
	v_pk_mul_f32 v[186:187], v[44:45], v[186:187]
	v_pk_mul_f32 v[188:189], v[46:47], v[188:189]
	v_pk_mul_f32 v[182:183], v[48:49], v[182:183]
	v_pk_mul_f32 v[184:185], v[50:51], v[184:185]
	v_pk_mul_f32 v[186:187], v[40:41], v[186:187]
	v_pk_mul_f32 v[188:189], v[42:43], v[188:189]
	v_cvt_pk_bf16_f32 v0, v182, v183
	v_cvt_pk_bf16_f32 v1, v184, v185
	v_cvt_pk_bf16_f32 v2, v186, v187
	v_cvt_pk_bf16_f32 v3, v188, v189
	v_lshl_add_u64 v[190:191], v[190:191], 0, v[192:193]
	global_store_dwordx4 v[190:191], v[0:3], off
	s_nop 1
	v_pk_mul_f32 v[36:37], v[36:37], v[6:7] op_sel_hi:[1,0]
	v_pk_mul_f32 v[38:39], v[38:39], v[6:7] op_sel_hi:[1,0]
	v_pk_mul_f32 v[28:29], v[28:29], v[6:7] op_sel_hi:[1,0]
	v_pk_mul_f32 v[30:31], v[30:31], v[6:7] op_sel_hi:[1,0]
	v_pk_mul_f32 v[32:33], v[32:33], v[6:7] op_sel_hi:[1,0]
	v_pk_mul_f32 v[34:35], v[34:35], v[6:7] op_sel_hi:[1,0]
	v_pk_mul_f32 v[24:25], v[24:25], v[6:7] op_sel_hi:[1,0]
	v_pk_mul_f32 v[26:27], v[26:27], v[6:7] op_sel_hi:[1,0]
	v_pk_mul_f32 v[182:183], v[36:37], s[100:101] op_sel_hi:[1,0]
	v_pk_mul_f32 v[184:185], v[38:39], s[100:101] op_sel_hi:[1,0]
	v_pk_mul_f32 v[186:187], v[28:29], s[100:101] op_sel_hi:[1,0]
	v_pk_mul_f32 v[188:189], v[30:31], s[100:101] op_sel_hi:[1,0]
	v_exp_f32_e32 v182, v182
	v_exp_f32_e32 v183, v183
	v_exp_f32_e32 v184, v184
	v_exp_f32_e32 v185, v185
	v_exp_f32_e32 v186, v186
	v_exp_f32_e32 v187, v187
	v_exp_f32_e32 v188, v188
	v_exp_f32_e32 v189, v189
	v_pk_add_f32 v[182:183], v[182:183], s[100:101] op_sel:[0,1]
	v_pk_add_f32 v[184:185], v[184:185], s[100:101] op_sel:[0,1]
	v_pk_add_f32 v[186:187], v[186:187], s[100:101] op_sel:[0,1]
	v_pk_add_f32 v[188:189], v[188:189], s[100:101] op_sel:[0,1]
	v_rcp_f32_e32 v182, v182
	v_rcp_f32_e32 v183, v183
	v_rcp_f32_e32 v184, v184
	v_rcp_f32_e32 v185, v185
	v_rcp_f32_e32 v186, v186
	v_rcp_f32_e32 v187, v187
	v_rcp_f32_e32 v188, v188
	v_rcp_f32_e32 v189, v189
	v_pk_mul_f32 v[182:183], v[36:37], v[182:183]
	v_pk_mul_f32 v[184:185], v[38:39], v[184:185]
	v_pk_mul_f32 v[186:187], v[28:29], v[186:187]
	v_pk_mul_f32 v[188:189], v[30:31], v[188:189]
	v_pk_mul_f32 v[182:183], v[32:33], v[182:183]
	v_pk_mul_f32 v[184:185], v[34:35], v[184:185]
	v_pk_mul_f32 v[186:187], v[24:25], v[186:187]
	v_pk_mul_f32 v[188:189], v[26:27], v[188:189]
	v_cvt_pk_bf16_f32 v0, v182, v183
	v_cvt_pk_bf16_f32 v1, v184, v185
	v_cvt_pk_bf16_f32 v2, v186, v187
	v_cvt_pk_bf16_f32 v3, v188, v189
	v_lshl_add_u64 v[190:191], v[190:191], 0, v[192:193]
	global_store_dwordx4 v[190:191], v[0:3], off
	s_nop 1
	v_pk_mul_f32 v[20:21], v[20:21], v[6:7] op_sel:[0,1]
	v_pk_mul_f32 v[22:23], v[22:23], v[6:7] op_sel:[0,1]
	v_pk_mul_f32 v[12:13], v[12:13], v[6:7] op_sel:[0,1]
	v_pk_mul_f32 v[14:15], v[14:15], v[6:7] op_sel:[0,1]
	v_pk_mul_f32 v[16:17], v[16:17], v[6:7] op_sel:[0,1]
	v_pk_mul_f32 v[18:19], v[18:19], v[6:7] op_sel:[0,1]
	v_pk_mul_f32 v[8:9], v[8:9], v[6:7] op_sel:[0,1]
	v_pk_mul_f32 v[10:11], v[10:11], v[6:7] op_sel:[0,1]
	v_pk_mul_f32 v[182:183], v[20:21], s[100:101] op_sel_hi:[1,0]
	v_pk_mul_f32 v[184:185], v[22:23], s[100:101] op_sel_hi:[1,0]
	v_pk_mul_f32 v[186:187], v[12:13], s[100:101] op_sel_hi:[1,0]
	v_pk_mul_f32 v[188:189], v[14:15], s[100:101] op_sel_hi:[1,0]
	v_exp_f32_e32 v182, v182
	v_exp_f32_e32 v183, v183
	v_exp_f32_e32 v184, v184
	v_exp_f32_e32 v185, v185
	v_exp_f32_e32 v186, v186
	v_exp_f32_e32 v187, v187
	v_exp_f32_e32 v188, v188
	v_exp_f32_e32 v189, v189
	v_pk_add_f32 v[182:183], v[182:183], s[100:101] op_sel:[0,1]
	v_pk_add_f32 v[184:185], v[184:185], s[100:101] op_sel:[0,1]
	v_pk_add_f32 v[186:187], v[186:187], s[100:101] op_sel:[0,1]
	v_pk_add_f32 v[188:189], v[188:189], s[100:101] op_sel:[0,1]
	v_rcp_f32_e32 v182, v182
	v_rcp_f32_e32 v183, v183
	v_rcp_f32_e32 v184, v184
	v_rcp_f32_e32 v185, v185
	v_rcp_f32_e32 v186, v186
	v_rcp_f32_e32 v187, v187
	v_rcp_f32_e32 v188, v188
	v_rcp_f32_e32 v189, v189
	v_pk_mul_f32 v[182:183], v[20:21], v[182:183]
	v_pk_mul_f32 v[184:185], v[22:23], v[184:185]
	v_pk_mul_f32 v[186:187], v[12:13], v[186:187]
	v_pk_mul_f32 v[188:189], v[14:15], v[188:189]
	v_pk_mul_f32 v[182:183], v[16:17], v[182:183]
	v_pk_mul_f32 v[184:185], v[18:19], v[184:185]
	v_pk_mul_f32 v[186:187], v[8:9], v[186:187]
	v_pk_mul_f32 v[188:189], v[10:11], v[188:189]
	v_cvt_pk_bf16_f32 v0, v182, v183
	v_cvt_pk_bf16_f32 v1, v184, v185
	v_cvt_pk_bf16_f32 v2, v186, v187
	v_cvt_pk_bf16_f32 v3, v188, v189
	v_lshl_add_u64 v[190:191], v[190:191], 0, v[192:193]
	s_mov_b64 s[22:23], -1
	global_store_dwordx4 v[190:191], v[0:3], off
	s_nop 1
	s_cbranch_vccnz .LBB0_93
	s_andn2_b64 vcc, exec, s[8:9]
	s_cbranch_vccnz .LBB0_92
	s_barrier
	s_branch .LBB0_92
